# v64 + nt on the P0 input-row loads and the final-phase loads (each read once)
# baseline (speedup 1.0000x reference)
.LBB0_140:
	global_load_dwordx4 v[156:159], v[164:165], off offset:-4096 nt
	global_load_dwordx4 v[152:155], v[164:165], off offset:-4080 nt
	global_load_dwordx4 v[140:143], v[164:165], off offset:16 nt
	global_load_dwordx4 v[148:151], v[164:165], off nt
	global_load_dwordx4 v[144:147], v[164:165], off offset:-2048 nt
	s_waitcnt lgkmcnt(0)
	global_load_dwordx4 v[136:139], v[164:165], off offset:-2032 nt
	global_load_dwordx4 v[132:135], v[164:165], off offset:2048 nt
	global_load_dwordx4 v[128:131], v[164:165], off offset:2064 nt
	s_waitcnt vmcnt(7)
	v_pk_mul_f32 v[176:177], v[158:159], v[158:159]
	v_pk_mul_f32 v[182:183], v[156:157], v[156:157]
	s_waitcnt vmcnt(6)
	v_pk_mul_f32 v[184:185], v[154:155], v[154:155]
	v_pk_mul_f32 v[186:187], v[152:153], v[152:153]
	s_waitcnt vmcnt(5)
	v_pk_mul_f32 v[188:189], v[142:143], v[142:143]
	v_pk_mul_f32 v[190:191], v[140:141], v[140:141]
	s_waitcnt vmcnt(4)
	v_pk_mul_f32 v[192:193], v[150:151], v[150:151]
	v_pk_mul_f32 v[194:195], v[148:149], v[148:149]
	v_pk_mov_b32 v[200:201], v[182:183], v[176:177] op_sel:[1,0]
	v_mov_b32_e32 v183, v177
	v_pk_mov_b32 v[176:177], v[186:187], v[184:185] op_sel:[1,0]
	v_mov_b32_e32 v187, v185
	v_pk_mov_b32 v[184:185], v[190:191], v[188:189] op_sel:[1,0]
	v_mov_b32_e32 v191, v189
	v_pk_mov_b32 v[188:189], v[194:195], v[192:193] op_sel:[1,0]
	v_mov_b32_e32 v195, v193
	s_waitcnt vmcnt(3)
	v_mul_f32_e32 v168, v145, v145
	v_mul_f32_e32 v178, v147, v147
	s_waitcnt vmcnt(1)
	v_mul_f32_e32 v196, v133, v133
	v_mul_f32_e32 v198, v135, v135
	s_waitcnt lgkmcnt(11)
	v_mul_f32_e32 v179, v157, v81
	v_pk_add_f32 v[182:183], v[200:201], v[182:183]
	v_pk_add_f32 v[176:177], v[176:177], v[186:187]
	v_pk_add_f32 v[184:185], v[184:185], v[190:191]
	v_pk_add_f32 v[186:187], v[188:189], v[194:195]
	v_mul_f32_e32 v175, v138, v138
	v_mul_f32_e32 v181, v139, v139
	s_waitcnt vmcnt(0)
	v_mul_f32_e32 v205, v130, v130
	v_mul_f32_e32 v206, v131, v131
	v_mul_f32_e32 v207, v136, v136
	v_mul_f32_e32 v208, v137, v137
	v_mul_f32_e32 v209, v128, v128
	v_mul_f32_e32 v210, v129, v129
	v_pk_fma_f32 v[192:193], v[144:145], v[144:145], v[168:169] op_sel_hi:[1,1,0]
	v_pk_fma_f32 v[202:203], v[146:147], v[146:147], v[178:179] op_sel_hi:[1,1,0]
	v_pk_fma_f32 v[196:197], v[132:133], v[132:133], v[196:197] op_sel_hi:[1,1,0]
	v_pk_fma_f32 v[198:199], v[134:135], v[134:135], v[198:199] op_sel_hi:[1,1,0]
	v_pk_add_f32 v[182:183], v[182:183], v[182:183] op_sel:[0,1] op_sel_hi:[1,0]
	v_pk_add_f32 v[176:177], v[176:177], v[176:177] op_sel:[0,1] op_sel_hi:[1,0]
	v_pk_add_f32 v[186:187], v[186:187], v[186:187] op_sel:[0,1] op_sel_hi:[1,0]
	v_pk_add_f32 v[184:185], v[184:185], v[184:185] op_sel:[0,1] op_sel_hi:[1,0]
	v_mov_b32_e32 v193, v175
	v_mov_b32_e32 v203, v181
	v_mov_b32_e32 v197, v205
	v_mov_b32_e32 v199, v206
	v_mov_b32_e32 v183, v207
	v_mov_b32_e32 v177, v208
	v_mov_b32_e32 v187, v209
	v_mov_b32_e32 v185, v210
	v_pk_add_f32 v[188:189], v[192:193], v[202:203]
	v_pk_add_f32 v[190:191], v[196:197], v[198:199]
	v_pk_add_f32 v[176:177], v[182:183], v[176:177]
	v_pk_add_f32 v[182:183], v[186:187], v[184:185]
	v_pk_add_f32 v[176:177], v[176:177], v[188:189]
	v_pk_add_f32 v[182:183], v[182:183], v[190:191]
	v_mov_b32_e32 v185, v176
	v_mov_b32_e32 v184, v182
	v_mov_b32_e32 v176, v183
	v_pk_add_f32 v[182:183], v[184:185], v[176:177]
	ds_bpermute_b32 v185, v169, v183
	ds_bpermute_b32 v184, v169, v182
	v_mul_f32_e32 v211, v157, v1
	v_mul_f32_e32 v212, v159, v3
	v_mul_f32_e32 v213, v157, v17
	v_mul_f32_e32 v214, v159, v19
	s_waitcnt lgkmcnt(0)
	v_pk_add_f32 v[182:183], v[182:183], v[184:185]
	ds_bpermute_b32 v185, v170, v183
	ds_bpermute_b32 v184, v170, v182
	v_mul_f32_e32 v215, v157, v33
	v_mul_f32_e32 v216, v159, v35
	v_mul_f32_e32 v217, v157, v49
	v_mul_f32_e32 v218, v159, v51
	s_waitcnt lgkmcnt(0)
	v_pk_add_f32 v[182:183], v[182:183], v[184:185]
	ds_bpermute_b32 v185, v171, v183
	ds_bpermute_b32 v184, v171, v182
	v_mul_f32_e32 v219, v157, v65
	v_mul_f32_e32 v220, v159, v67
	v_mul_f32_e32 v180, v159, v83
	v_mul_f32_e32 v177, v157, v97
	s_waitcnt lgkmcnt(0)
	v_pk_add_f32 v[182:183], v[182:183], v[184:185]
	ds_bpermute_b32 v185, v172, v183
	ds_bpermute_b32 v184, v172, v182
	v_mul_f32_e32 v178, v159, v99
	v_mul_f32_e32 v175, v157, v113
	v_mul_f32_e32 v176, v159, v115
	v_fmac_f32_e32 v211, v156, v0
	s_waitcnt lgkmcnt(0)
	v_pk_add_f32 v[182:183], v[182:183], v[184:185]
	ds_bpermute_b32 v185, v173, v183
	ds_bpermute_b32 v184, v173, v182
	v_fmac_f32_e32 v212, v158, v2
	v_fmac_f32_e32 v213, v156, v16
	v_fmac_f32_e32 v214, v158, v18
	v_fmac_f32_e32 v215, v156, v32
	s_waitcnt lgkmcnt(0)
	v_pk_add_f32 v[182:183], v[182:183], v[184:185]
	ds_bpermute_b32 v185, v174, v183
	ds_bpermute_b32 v184, v174, v182
	v_fmac_f32_e32 v216, v158, v34
	v_fmac_f32_e32 v217, v156, v48
	v_fmac_f32_e32 v218, v158, v50
	v_fmac_f32_e32 v219, v156, v64
	s_waitcnt lgkmcnt(0)
	v_pk_add_f32 v[182:183], v[182:183], v[184:185]
	v_fmac_f32_e32 v220, v158, v66
	v_pk_fma_f32 v[186:187], v[182:183], s[28:29], v[166:167] op_sel_hi:[1,0,0]
	v_fmac_f32_e32 v179, v156, v80
	v_mul_f32_e32 v168, 0x4b800000, v187
	v_cmp_gt_f32_e64 s[10:11], s17, v187
	v_fmac_f32_e32 v180, v158, v82
	v_fmac_f32_e32 v177, v156, v96
	v_cndmask_b32_e64 v168, v187, v168, s[10:11]
	v_rsq_f32_e32 v168, v168
	v_fmac_f32_e32 v178, v158, v98
	v_fmac_f32_e32 v175, v156, v112
	v_fmac_f32_e32 v176, v158, v114
	v_mul_f32_e32 v182, 0x45800000, v168
	v_cndmask_b32_e64 v168, v168, v182, s[10:11]
	v_pk_mul_f32 v[156:157], v[156:157], v[168:169] op_sel_hi:[1,0]
	v_pk_mul_f32 v[158:159], v[158:159], v[168:169] op_sel_hi:[1,0]
	v_mul_f32_e32 v181, v153, v5
	v_mul_f32_e32 v189, v153, v21
	v_cvt_pk_bf16_f32 v182, v156, v157
	v_cvt_pk_bf16_f32 v183, v158, v159
	v_mul_f32_e32 v157, v153, v37
	v_mul_f32_e32 v159, v153, v53
	v_mul_f32_e32 v191, v153, v69
	v_mul_f32_e32 v193, v153, v85
	v_mul_f32_e32 v195, v153, v101
	v_mul_f32_e32 v156, v153, v117
	v_fmac_f32_e32 v181, v152, v4
	v_fmac_f32_e32 v189, v152, v20
	v_pk_mul_f32 v[184:185], v[152:153], v[168:169] op_sel_hi:[1,0]
	v_fmac_f32_e32 v157, v152, v36
	v_fmac_f32_e32 v159, v152, v52
	v_fmac_f32_e32 v191, v152, v68
	v_fmac_f32_e32 v193, v152, v84
	v_fmac_f32_e32 v195, v152, v100
	v_fmac_f32_e32 v156, v152, v116
	v_pk_mul_f32 v[152:153], v[154:155], v[168:169] op_sel_hi:[1,0]
	v_cvt_pk_bf16_f32 v184, v184, v185
	v_cvt_pk_bf16_f32 v185, v152, v153
	v_lshl_add_u64 v[152:153], s[88:89], 0, v[162:163]
	v_add_co_u32_e64 v152, s[10:11], s19, v152
	v_mul_f32_e32 v188, v155, v7
	v_mul_f32_e32 v190, v155, v23
	v_mul_f32_e32 v158, v155, v39
	v_mul_f32_e32 v187, v155, v55
	v_mul_f32_e32 v192, v155, v71
	v_mul_f32_e32 v194, v155, v87
	v_mul_f32_e32 v196, v155, v103
	v_mul_f32_e32 v197, v155, v119
	v_addc_co_u32_e64 v153, s[10:11], 0, v153, s[10:11]
	v_fmac_f32_e32 v188, v154, v6
	v_fmac_f32_e32 v190, v154, v22
	v_fmac_f32_e32 v158, v154, v38
	v_fmac_f32_e32 v187, v154, v54
	v_fmac_f32_e32 v192, v154, v70
	v_fmac_f32_e32 v194, v154, v86
	v_fmac_f32_e32 v196, v154, v102
	v_fmac_f32_e32 v197, v154, v118
	v_mul_f32_e32 v154, 0x4b800000, v186
	v_cmp_gt_f32_e64 s[10:11], s17, v186
	v_mul_f32_e32 v155, v149, v1
	global_store_dwordx4 v[152:153], v[182:185], off
	v_cndmask_b32_e64 v154, v186, v154, s[10:11]
	v_rsq_f32_e32 v154, v154
	v_fmac_f32_e32 v155, v148, v0
	v_mul_f32_e32 v182, v151, v3
	v_mul_f32_e32 v183, v149, v17
	v_mul_f32_e32 v209, 0x45800000, v154
	v_mul_f32_e32 v184, v151, v19
	v_mul_f32_e32 v185, v149, v33
	v_mul_f32_e32 v186, v151, v35
	v_mul_f32_e32 v198, v149, v49
	v_mul_f32_e32 v199, v151, v51
	v_mul_f32_e32 v200, v149, v65
	v_mul_f32_e32 v201, v151, v67
	v_mul_f32_e32 v202, v149, v81
	v_mul_f32_e32 v203, v151, v83
	v_mul_f32_e32 v205, v149, v97
	v_mul_f32_e32 v206, v151, v99
	v_mul_f32_e32 v207, v149, v113
	v_mul_f32_e32 v208, v151, v115
	v_cndmask_b32_e64 v154, v154, v209, s[10:11]
	v_fmac_f32_e32 v182, v150, v2
	v_fmac_f32_e32 v183, v148, v16
	v_fmac_f32_e32 v184, v150, v18
	v_fmac_f32_e32 v185, v148, v32
	v_fmac_f32_e32 v186, v150, v34
	v_fmac_f32_e32 v198, v148, v48
	v_fmac_f32_e32 v199, v150, v50
	v_fmac_f32_e32 v200, v148, v64
	v_fmac_f32_e32 v201, v150, v66
	v_fmac_f32_e32 v202, v148, v80
	v_fmac_f32_e32 v203, v150, v82
	v_fmac_f32_e32 v205, v148, v96
	v_fmac_f32_e32 v206, v150, v98
	v_fmac_f32_e32 v207, v148, v112
	v_fmac_f32_e32 v208, v150, v114
	v_pk_mul_f32 v[148:149], v[148:149], v[154:155] op_sel_hi:[1,0]
	v_pk_mul_f32 v[150:151], v[150:151], v[154:155] op_sel_hi:[1,0]
	v_cvt_pk_bf16_f32 v148, v148, v149
	v_cvt_pk_bf16_f32 v149, v150, v151
	v_pk_mul_f32 v[150:151], v[140:141], v[154:155] op_sel_hi:[1,0]
	v_mul_f32_e32 v209, v143, v7
	v_cvt_pk_bf16_f32 v150, v150, v151
	v_mul_f32_e32 v151, v141, v5
	v_mul_f32_e32 v210, v141, v21
	v_mul_f32_e32 v221, v143, v23
	v_mul_f32_e32 v222, v141, v37
	v_mul_f32_e32 v223, v143, v39
	v_mul_f32_e32 v224, v141, v53
	v_mul_f32_e32 v225, v143, v55
	v_mul_f32_e32 v226, v141, v69
	v_mul_f32_e32 v227, v143, v71
	v_mul_f32_e32 v228, v141, v85
	v_mul_f32_e32 v229, v143, v87
	v_mul_f32_e32 v230, v141, v101
	v_mul_f32_e32 v231, v143, v103
	v_mul_f32_e32 v232, v141, v117
	v_mul_f32_e32 v233, v143, v119
	v_fmac_f32_e32 v151, v140, v4
	v_fmac_f32_e32 v209, v142, v6
	v_fmac_f32_e32 v210, v140, v20
	v_fmac_f32_e32 v221, v142, v22
	v_fmac_f32_e32 v222, v140, v36
	v_fmac_f32_e32 v223, v142, v38
	v_fmac_f32_e32 v224, v140, v52
	v_fmac_f32_e32 v225, v142, v54
	v_fmac_f32_e32 v226, v140, v68
	v_fmac_f32_e32 v227, v142, v70
	v_fmac_f32_e32 v228, v140, v84
	v_fmac_f32_e32 v229, v142, v86
	v_fmac_f32_e32 v230, v140, v100
	v_fmac_f32_e32 v231, v142, v102
	v_fmac_f32_e32 v232, v140, v116
	v_fmac_f32_e32 v233, v142, v118
	v_pk_mul_f32 v[140:141], v[142:143], v[154:155] op_sel_hi:[1,0]
	v_mul_f32_e32 v142, v145, v9
	v_mul_f32_e32 v143, v147, v11
	v_add_f32_e32 v155, v155, v182
	v_fmac_f32_e32 v142, v144, v8
	v_fmac_f32_e32 v143, v146, v10
	v_add_f32_e32 v151, v151, v209
	v_add_f32_e32 v155, 0, v155
	v_add_f32_e32 v151, v155, v151
	v_add_f32_e32 v142, v142, v143
	v_mul_f32_e32 v143, v133, v9
	v_mul_f32_e32 v155, v135, v11
	v_fmac_f32_e32 v143, v132, v8
	v_fmac_f32_e32 v155, v134, v10
	v_add_f32_e32 v211, v211, v212
	v_add_f32_e32 v143, v143, v155
	v_add_f32_e32 v181, v181, v188
	v_add_f32_e32 v182, 0, v211
	v_add_f32_e32 v143, v151, v143
	v_mul_f32_e32 v151, v137, v13
	v_mul_f32_e32 v155, v139, v15
	v_add_f32_e32 v181, v182, v181
	v_fmac_f32_e32 v151, v136, v12
	v_fmac_f32_e32 v155, v138, v14
	v_add_f32_e32 v142, v181, v142
	v_add_f32_e32 v151, v151, v155
	v_add_f32_e32 v142, v142, v151
	v_mul_f32_e32 v151, v129, v13
	v_mul_f32_e32 v155, v131, v15
	v_fmac_f32_e32 v151, v128, v12
	v_fmac_f32_e32 v155, v130, v14
	v_add_f32_e32 v151, v151, v155
	v_add_f32_e32 v143, v143, v151
	v_add_f32_e32 v151, v213, v214
	v_mul_f32_e32 v234, v145, v25
	v_mul_f32_e32 v235, v147, v27
	v_add_f32_e32 v155, v183, v184
	v_add_f32_e32 v181, v189, v190
	v_add_f32_e32 v151, 0, v151
	v_fmac_f32_e32 v234, v144, v24
	v_fmac_f32_e32 v235, v146, v26
	v_add_f32_e32 v151, v151, v181
	v_add_f32_e32 v181, v210, v221
	v_add_f32_e32 v155, 0, v155
	v_add_f32_e32 v155, v155, v181
	v_add_f32_e32 v181, v234, v235
	v_add_f32_e32 v151, v151, v181
	v_mul_f32_e32 v181, v133, v25
	v_mul_f32_e32 v182, v135, v27
	v_fmac_f32_e32 v181, v132, v24
	v_fmac_f32_e32 v182, v134, v26
	v_add_f32_e32 v181, v181, v182
	v_add_f32_e32 v155, v155, v181
	v_mul_f32_e32 v181, v137, v29
	v_mul_f32_e32 v182, v139, v31
	v_fmac_f32_e32 v181, v136, v28
	v_fmac_f32_e32 v182, v138, v30
	v_add_f32_e32 v181, v181, v182
	v_add_f32_e32 v151, v151, v181
	v_mul_f32_e32 v181, v129, v29
	v_mul_f32_e32 v182, v131, v31
	v_fmac_f32_e32 v181, v128, v28
	v_fmac_f32_e32 v182, v130, v30
	v_add_f32_e32 v181, v181, v182
	v_add_f32_e32 v155, v155, v181
	v_add_f32_e32 v181, v215, v216
	v_mul_f32_e32 v236, v145, v41
	v_mul_f32_e32 v237, v147, v43
	v_add_f32_e32 v182, v185, v186
	v_add_f32_e32 v157, v157, v158
	v_add_f32_e32 v158, 0, v181
	v_fmac_f32_e32 v236, v144, v40
	v_fmac_f32_e32 v237, v146, v42
	v_add_f32_e32 v157, v158, v157
	v_add_f32_e32 v158, v222, v223
	v_add_f32_e32 v181, 0, v182
	v_add_f32_e32 v158, v181, v158
	v_add_f32_e32 v181, v236, v237
	v_add_f32_e32 v157, v157, v181
	v_mul_f32_e32 v181, v133, v41
	v_mul_f32_e32 v182, v135, v43
	v_fmac_f32_e32 v181, v132, v40
	v_fmac_f32_e32 v182, v134, v42
	v_add_f32_e32 v181, v181, v182
	v_add_f32_e32 v158, v158, v181
	v_mul_f32_e32 v181, v137, v45
	v_mul_f32_e32 v182, v139, v47
	v_fmac_f32_e32 v181, v136, v44
	v_fmac_f32_e32 v182, v138, v46
	v_add_f32_e32 v181, v181, v182
	v_add_f32_e32 v157, v157, v181
	v_mul_f32_e32 v181, v129, v45
	v_mul_f32_e32 v182, v131, v47
	v_fmac_f32_e32 v181, v128, v44
	v_fmac_f32_e32 v182, v130, v46
	v_add_f32_e32 v181, v181, v182
	v_add_f32_e32 v158, v158, v181
	v_add_f32_e32 v181, v217, v218
	v_mul_f32_e32 v238, v145, v57
	v_mul_f32_e32 v239, v147, v59
	v_add_f32_e32 v182, v198, v199
	v_add_f32_e32 v159, v159, v187
	v_add_f32_e32 v181, 0, v181
	v_fmac_f32_e32 v238, v144, v56
	v_fmac_f32_e32 v239, v146, v58
	v_add_f32_e32 v159, v181, v159
	v_add_f32_e32 v181, v224, v225
	v_add_f32_e32 v182, 0, v182
	v_add_f32_e32 v181, v182, v181
	v_add_f32_e32 v182, v238, v239
	v_add_f32_e32 v159, v159, v182
	v_mul_f32_e32 v182, v133, v57
	v_mul_f32_e32 v183, v135, v59
	v_fmac_f32_e32 v182, v132, v56
	v_fmac_f32_e32 v183, v134, v58
	v_add_f32_e32 v182, v182, v183
	v_add_f32_e32 v181, v181, v182
	v_mul_f32_e32 v182, v137, v61
	v_mul_f32_e32 v183, v139, v63
	v_fmac_f32_e32 v182, v136, v60
	v_fmac_f32_e32 v183, v138, v62
	v_add_f32_e32 v182, v182, v183
	v_add_f32_e32 v159, v159, v182
	v_mul_f32_e32 v182, v129, v61
	v_mul_f32_e32 v183, v131, v63
	v_fmac_f32_e32 v182, v128, v60
	v_fmac_f32_e32 v183, v130, v62
	v_add_f32_e32 v182, v182, v183
	v_add_f32_e32 v181, v181, v182
	v_add_f32_e32 v182, v219, v220
	v_mul_f32_e32 v240, v145, v73
	v_mul_f32_e32 v241, v147, v75
	v_add_f32_e32 v183, v200, v201
	v_add_f32_e32 v184, v191, v192
	v_add_f32_e32 v182, 0, v182
	v_fmac_f32_e32 v240, v144, v72
	v_fmac_f32_e32 v241, v146, v74
	v_add_f32_e32 v182, v182, v184
	v_add_f32_e32 v184, v226, v227
	v_add_f32_e32 v183, 0, v183
	v_add_f32_e32 v183, v183, v184
	v_add_f32_e32 v184, v240, v241
	v_add_f32_e32 v182, v182, v184
	v_mul_f32_e32 v184, v133, v73
	v_mul_f32_e32 v185, v135, v75
	v_fmac_f32_e32 v184, v132, v72
	v_fmac_f32_e32 v185, v134, v74
	v_add_f32_e32 v184, v184, v185
	v_add_f32_e32 v183, v183, v184
	v_mul_f32_e32 v184, v137, v77
	v_mul_f32_e32 v185, v139, v79
	v_fmac_f32_e32 v184, v136, v76
	v_fmac_f32_e32 v185, v138, v78
	v_add_f32_e32 v184, v184, v185
	v_add_f32_e32 v182, v182, v184
	v_mul_f32_e32 v184, v129, v77
	v_mul_f32_e32 v185, v131, v79
	v_fmac_f32_e32 v184, v128, v76
	v_fmac_f32_e32 v185, v130, v78
	v_add_f32_e32 v184, v184, v185
	v_add_f32_e32 v179, v179, v180
	v_mul_f32_e32 v242, v145, v89
	v_mul_f32_e32 v243, v147, v91
	v_add_f32_e32 v183, v183, v184
	v_add_f32_e32 v180, v202, v203
	v_add_f32_e32 v184, v193, v194
	v_add_f32_e32 v179, 0, v179
	v_fmac_f32_e32 v242, v144, v88
	v_fmac_f32_e32 v243, v146, v90
	v_add_f32_e32 v179, v179, v184
	v_add_f32_e32 v184, v228, v229
	v_add_f32_e32 v180, 0, v180
	v_add_f32_e32 v180, v180, v184
	v_add_f32_e32 v184, v242, v243
	v_add_f32_e32 v179, v179, v184
	v_mul_f32_e32 v184, v133, v89
	v_mul_f32_e32 v185, v135, v91
	v_fmac_f32_e32 v184, v132, v88
	v_fmac_f32_e32 v185, v134, v90
	v_add_f32_e32 v184, v184, v185
	v_add_f32_e32 v180, v180, v184
	v_mul_f32_e32 v184, v137, v93
	v_mul_f32_e32 v185, v139, v95
	v_fmac_f32_e32 v184, v136, v92
	v_fmac_f32_e32 v185, v138, v94
	v_add_f32_e32 v184, v184, v185
	v_add_f32_e32 v179, v179, v184
	v_mul_f32_e32 v184, v129, v93
	v_mul_f32_e32 v185, v131, v95
	v_fmac_f32_e32 v184, v128, v92
	v_fmac_f32_e32 v185, v130, v94
	v_add_f32_e32 v184, v184, v185
	v_add_f32_e32 v177, v177, v178
	v_mul_f32_e32 v244, v145, v105
	v_mul_f32_e32 v245, v147, v107
	v_add_f32_e32 v180, v180, v184
	v_add_f32_e32 v178, v205, v206
	v_add_f32_e32 v184, v195, v196
	v_add_f32_e32 v177, 0, v177
	v_fmac_f32_e32 v244, v144, v104
	v_fmac_f32_e32 v245, v146, v106
	v_add_f32_e32 v177, v177, v184
	v_add_f32_e32 v184, v230, v231
	v_add_f32_e32 v178, 0, v178
	v_add_f32_e32 v178, v178, v184
	v_add_f32_e32 v184, v244, v245
	v_add_f32_e32 v177, v177, v184
	v_mul_f32_e32 v184, v133, v105
	v_mul_f32_e32 v185, v135, v107
	v_fmac_f32_e32 v184, v132, v104
	v_fmac_f32_e32 v185, v134, v106
	v_add_f32_e32 v184, v184, v185
	v_add_f32_e32 v178, v178, v184
	v_mul_f32_e32 v184, v137, v109
	v_mul_f32_e32 v185, v139, v111
	v_fmac_f32_e32 v184, v136, v108
	v_fmac_f32_e32 v185, v138, v110
	v_add_f32_e32 v184, v184, v185
	v_add_f32_e32 v175, v175, v176
	v_mul_f32_e32 v246, v145, v121
	v_mul_f32_e32 v247, v147, v123
	v_add_f32_e32 v177, v177, v184
	v_mul_f32_e32 v184, v129, v109
	v_mul_f32_e32 v185, v131, v111
	v_add_f32_e32 v176, v207, v208
	v_add_f32_e32 v156, v156, v197
	v_add_f32_e32 v175, 0, v175
	v_fmac_f32_e32 v246, v144, v120
	v_fmac_f32_e32 v247, v146, v122
	v_fmac_f32_e32 v184, v128, v108
	v_fmac_f32_e32 v185, v130, v110
	v_add_f32_e32 v156, v175, v156
	v_add_f32_e32 v175, v232, v233
	v_add_f32_e32 v176, 0, v176
	v_add_f32_e32 v184, v184, v185
	v_add_f32_e32 v175, v176, v175
	v_add_f32_e32 v176, v246, v247
	v_add_f32_e32 v178, v178, v184
	v_add_f32_e32 v156, v156, v176
	v_mul_f32_e32 v176, v133, v121
	v_mul_f32_e32 v184, v135, v123
	v_fmac_f32_e32 v176, v132, v120
	v_fmac_f32_e32 v184, v134, v122
	v_add_f32_e32 v176, v176, v184
	v_add_f32_e32 v175, v175, v176
	v_mul_f32_e32 v176, v137, v125
	v_mul_f32_e32 v184, v139, v127
	v_fmac_f32_e32 v176, v136, v124
	v_fmac_f32_e32 v184, v138, v126
	v_add_f32_e32 v176, v176, v184
	v_add_f32_e32 v156, v156, v176
	v_mul_f32_e32 v176, v129, v125
	v_mul_f32_e32 v184, v131, v127
	v_fmac_f32_e32 v176, v128, v124
	v_fmac_f32_e32 v184, v130, v126
	v_add_f32_e32 v176, v176, v184
	v_add_f32_e32 v175, v175, v176
	v_cndmask_b32_e32 v176, v142, v143, vcc
	v_cndmask_b32_e32 v142, v143, v142, vcc
	ds_bpermute_b32 v143, v174, v176
	v_cndmask_b32_e32 v176, v151, v155, vcc
	v_cndmask_b32_e32 v184, v157, v158, vcc
	ds_bpermute_b32 v176, v174, v176
	ds_bpermute_b32 v184, v174, v184
	s_waitcnt lgkmcnt(2)
	v_add_f32_e32 v142, v142, v143
	v_cndmask_b32_e32 v143, v155, v151, vcc
	v_cndmask_b32_e32 v155, v159, v181, vcc
	v_cndmask_b32_e32 v151, v158, v157, vcc
	ds_bpermute_b32 v155, v174, v155
	v_cndmask_b32_e32 v158, v182, v183, vcc
	v_cndmask_b32_e32 v157, v181, v159, vcc
	ds_bpermute_b32 v158, v174, v158
	v_cndmask_b32_e32 v159, v179, v180, vcc
	ds_bpermute_b32 v159, v174, v159
	s_waitcnt lgkmcnt(2)
	v_add_f32_e32 v155, v157, v155
	v_cndmask_b32_e32 v157, v183, v182, vcc
	s_waitcnt lgkmcnt(1)
	v_add_f32_e32 v157, v157, v158
	v_cndmask_b32_e32 v158, v180, v179, vcc
	s_waitcnt lgkmcnt(0)
	v_add_f32_e32 v158, v158, v159
	v_cndmask_b32_e32 v159, v177, v178, vcc
	v_add_f32_e32 v143, v143, v176
	v_cndmask_b32_e32 v176, v178, v177, vcc
	ds_bpermute_b32 v159, v174, v159
	v_cndmask_b32_e32 v177, v156, v175, vcc
	ds_bpermute_b32 v177, v174, v177
	v_add_f32_e32 v151, v151, v184
	v_cndmask_b32_e32 v156, v175, v156, vcc
	s_waitcnt lgkmcnt(1)
	v_add_f32_e32 v159, v176, v159
	v_cndmask_b32_e64 v178, v142, v157, s[0:1]
	s_waitcnt lgkmcnt(0)
	v_add_f32_e32 v156, v156, v177
	v_cndmask_b32_e64 v142, v157, v142, s[0:1]
	v_cndmask_b32_e64 v157, v143, v158, s[0:1]
	v_cndmask_b32_e64 v143, v158, v143, s[0:1]
	v_cndmask_b32_e64 v158, v151, v159, s[0:1]
	ds_bpermute_b32 v178, v173, v178
	ds_bpermute_b32 v157, v173, v157
	ds_bpermute_b32 v158, v173, v158
	v_cndmask_b32_e64 v175, v155, v156, s[0:1]
	ds_bpermute_b32 v175, v173, v175
	v_cndmask_b32_e64 v151, v159, v151, s[0:1]
	s_waitcnt lgkmcnt(3)
	v_add_f32_e32 v142, v142, v178
	s_waitcnt lgkmcnt(2)
	v_add_f32_e32 v143, v143, v157
	s_waitcnt lgkmcnt(1)
	v_add_f32_e32 v157, v151, v158
	v_cndmask_b32_e64 v151, v156, v155, s[0:1]
	s_waitcnt lgkmcnt(0)
	v_add_f32_e32 v155, v151, v175
	v_cndmask_b32_e64 v151, v142, v157, s[8:9]
	ds_bpermute_b32 v156, v172, v151
	v_cndmask_b32_e64 v151, v143, v155, s[8:9]
	ds_bpermute_b32 v158, v172, v151
	v_cvt_pk_bf16_f32 v151, v140, v141
	v_cndmask_b32_e64 v140, v157, v142, s[8:9]
	s_waitcnt lgkmcnt(1)
	v_add_f32_e32 v156, v140, v156
	v_cndmask_b32_e64 v140, v155, v143, s[8:9]
	s_waitcnt lgkmcnt(0)
	v_add_f32_e32 v155, v140, v158
	v_cndmask_b32_e64 v140, v156, v155, s[4:5]
	ds_bpermute_b32 v157, v171, v140
	v_pk_mul_f32 v[140:141], v[144:145], v[168:169] op_sel_hi:[1,0]
	v_cndmask_b32_e64 v144, v155, v156, s[4:5]
	v_pk_mul_f32 v[142:143], v[146:147], v[168:169] op_sel_hi:[1,0]
	v_pk_mul_f32 v[136:137], v[136:137], v[168:169] op_sel_hi:[1,0]
	s_waitcnt lgkmcnt(0)
	v_add_f32_e32 v144, v144, v157
	ds_bpermute_b32 v145, v170, v144
	v_cvt_pk_bf16_f32 v140, v140, v141
	v_cvt_pk_bf16_f32 v141, v142, v143
	v_cvt_pk_bf16_f32 v142, v136, v137
	v_pk_mul_f32 v[138:139], v[138:139], v[168:169] op_sel_hi:[1,0]
	s_waitcnt lgkmcnt(0)
	v_add_f32_e32 v136, v144, v145
	ds_bpermute_b32 v137, v169, v136
	v_pk_mul_f32 v[132:133], v[132:133], v[154:155] op_sel_hi:[1,0]
	v_pk_mul_f32 v[134:135], v[134:135], v[154:155] op_sel_hi:[1,0]
	v_pk_mul_f32 v[128:129], v[128:129], v[154:155] op_sel_hi:[1,0]
	v_cvt_pk_bf16_f32 v143, v138, v139
	v_cvt_pk_bf16_f32 v132, v132, v133
	v_cvt_pk_bf16_f32 v133, v134, v135
	v_cvt_pk_bf16_f32 v134, v128, v129
	v_pk_mul_f32 v[128:129], v[130:131], v[154:155] op_sel_hi:[1,0]
	global_store_dwordx4 v[152:153], v[148:151], off offset:2048
	v_cvt_pk_bf16_f32 v135, v128, v129
	global_store_dwordx4 v[152:153], v[140:143], off offset:1024
	global_store_dwordx4 v[152:153], v[132:135], off offset:3072
	s_and_saveexec_b64 s[10:11], s[6:7]
	s_cbranch_execz .LBB0_139
	v_cndmask_b32_e32 v128, v154, v168, vcc
	s_waitcnt lgkmcnt(0)
	v_add_f32_e32 v129, v136, v137
	v_mul_f32_e32 v130, v128, v129
	v_lshl_add_u64 v[128:129], s[88:89], 0, v[160:161]
	global_store_dword v[128:129], v130, off
	s_branch .LBB0_139

.LBB0_1238:
	s_add_u32 s12, s88, s0
	s_waitcnt vmcnt(0)
	v_lshl_add_u64 v[14:15], s[88:89], 0, v[4:5]
	s_addc_u32 s13, s89, s1
	v_add_co_u32_e32 v38, vcc, s10, v14
	global_load_dwordx4 v[10:13], v[2:3], off nt
	s_nop 0
	v_addc_co_u32_e32 v39, vcc, 0, v15, vcc
	global_load_dwordx4 v[14:17], v0, s[12:13]
	global_load_dwordx4 v[18:21], v[38:39], off nt
	s_add_u32 s12, s12, 0x1f000000
	s_addc_u32 s13, s13, 0
	global_load_dwordx4 v[22:25], v1, s[12:13] offset:16
	global_load_dwordx4 v[26:29], v1, s[12:13] offset:32
	global_load_dwordx4 v[30:33], v1, s[12:13] offset:48
	global_load_dwordx4 v[34:37], v[2:3], off offset:16 nt
	s_add_i32 s8, s8, s14
	s_add_u32 s0, s0, s2
	s_addc_u32 s1, s1, s3
	v_lshl_add_u64 v[4:5], v[4:5], 0, s[4:5]
	s_cmp_lt_i32 s8, 0x8000
	s_waitcnt vmcnt(5)
	v_mov_b32_e32 v40, v15
	v_mov_b32_e32 v41, v16
	v_mov_b32_e32 v15, v17
	v_pk_add_f32 v[14:15], v[40:41], v[14:15]
	s_waitcnt vmcnt(3)
	v_mov_b32_e32 v40, v23
	v_mov_b32_e32 v41, v24
	v_mov_b32_e32 v23, v25
	v_pk_add_f32 v[22:23], v[40:41], v[22:23]
	v_pk_add_f32 v[14:15], v[14:15], v[14:15] op_sel:[0,1] op_sel_hi:[1,0]
	v_pk_add_f32 v[22:23], v[22:23], v[22:23] op_sel:[0,1] op_sel_hi:[1,0]
	s_waitcnt vmcnt(2)
	v_add_f32_e32 v24, v26, v27
	v_add_f32_e32 v26, v28, v29
	s_waitcnt vmcnt(1)
	v_mov_b32_e32 v25, v32
	v_mov_b32_e32 v27, v33
	v_mov_b32_e32 v15, v30
	v_mov_b32_e32 v23, v31
	v_pk_add_f32 v[24:25], v[24:25], v[26:27]
	v_pk_add_f32 v[14:15], v[14:15], v[22:23]
	v_lshlrev_b32_e32 v16, 16, v18
	v_pk_add_f32 v[14:15], v[14:15], v[24:25]
	v_and_b32_e32 v17, 0xffff0000, v18
	v_add_f32_e32 v9, v14, v15
	v_fmamk_f32 v9, v9, 0x3a800000, v8
	v_mul_f32_e32 v14, 0x4b800000, v9
	v_cmp_gt_f32_e32 vcc, s9, v9
	v_lshlrev_b32_e32 v18, 16, v19
	v_and_b32_e32 v19, 0xffff0000, v19
	v_cndmask_b32_e32 v9, v9, v14, vcc
	v_rsq_f32_e32 v9, v9
	v_lshlrev_b32_e32 v42, 16, v20
	v_and_b32_e32 v43, 0xffff0000, v20
	v_lshlrev_b32_e32 v20, 16, v21
	v_mul_f32_e32 v14, 0x45800000, v9
	v_cndmask_b32_e32 v22, v9, v14, vcc
	v_and_b32_e32 v21, 0xffff0000, v21
	v_pk_mul_f32 v[14:15], v[22:23], v[16:17] op_sel_hi:[0,1]
	v_pk_mul_f32 v[16:17], v[22:23], v[18:19] op_sel_hi:[0,1]
	v_pk_mul_f32 v[18:19], v[22:23], v[42:43] op_sel_hi:[0,1]
	v_pk_mul_f32 v[20:21], v[22:23], v[20:21] op_sel_hi:[0,1]
	v_pk_mul_f32 v[10:11], v[10:11], v[14:15]
	v_pk_mul_f32 v[12:13], v[12:13], v[16:17]
	s_waitcnt vmcnt(0)
	v_pk_mul_f32 v[14:15], v[34:35], v[18:19]
	v_pk_mul_f32 v[16:17], v[36:37], v[20:21]
	global_store_dwordx4 v[6:7], v[10:13], off offset:-2064 nt
	global_store_dwordx4 v[6:7], v[14:17], off offset:-2048 nt
	global_load_dwordx4 v[10:13], v[38:39], off offset:1024 nt
	s_nop 0
	global_load_dwordx4 v[14:17], v[2:3], off offset:2048 nt
	global_load_dwordx4 v[18:21], v[2:3], off offset:2064 nt
	s_waitcnt vmcnt(2)
	v_lshlrev_b32_e32 v24, 16, v10
	v_and_b32_e32 v25, 0xffff0000, v10
	v_lshlrev_b32_e32 v10, 16, v11
	v_and_b32_e32 v11, 0xffff0000, v11
	v_lshlrev_b32_e32 v26, 16, v12
	v_and_b32_e32 v27, 0xffff0000, v12
	v_lshlrev_b32_e32 v12, 16, v13
	v_and_b32_e32 v13, 0xffff0000, v13
	v_pk_mul_f32 v[24:25], v[22:23], v[24:25] op_sel_hi:[0,1]
	v_pk_mul_f32 v[28:29], v[22:23], v[10:11] op_sel_hi:[0,1]
	v_pk_mul_f32 v[26:27], v[22:23], v[26:27] op_sel_hi:[0,1]
	v_pk_mul_f32 v[22:23], v[22:23], v[12:13] op_sel_hi:[0,1]
	s_waitcnt vmcnt(1)
	v_pk_mul_f32 v[10:11], v[14:15], v[24:25]
	v_pk_mul_f32 v[12:13], v[16:17], v[28:29]
	s_waitcnt vmcnt(0)
	v_pk_mul_f32 v[14:15], v[18:19], v[26:27]
	v_pk_mul_f32 v[16:17], v[20:21], v[22:23]
	global_store_dwordx4 v[6:7], v[10:13], off offset:-16 nt
	global_store_dwordx4 v[6:7], v[14:17], off nt
	v_lshl_add_u64 v[6:7], v[6:7], 0, s[6:7]
	s_cbranch_scc1 .LBB0_1238
